# P0 transposer weight loads sc0 sc1 nt (system scope, streaming) on top of s_sleep 80 pacing
# speedup vs baseline: 1.0058x; 1.0058x over previous
; __device__ __forceinline__ void t_load(const TItem& t, f32x4 (&v)[8]) {
; #pragma unroll
;     for (int j = 0; j < 8; ++j) v[j] = __builtin_nontemporal_load((const f32x4*)(t.src + (size_t)(8 * j) * t.N));
; }
; __device__ __forceinline__ void p0_prologue(const Ptrs& P, LAS unsigned char* lds, int vcu, int G, int tid) {
;     ...
;         TItem cur = t_decode(P, gw, lane); f32x4 v[8]; t_load(cur, v);
.LBB0_36:
	s_lshl_b32 s20, s39, 14
	s_mov_b32 s21, 0
	s_add_i32 s24, s20, 0
	s_mul_i32 s20, s22, 0xe0
	v_lshl_add_u64 v[10:11], v[34:35], 0, s[20:21]
	s_lshl_b32 s20, s22, 5
	s_sub_u32 s22, 0, s20
	s_subb_u32 s23, 0, 0
	v_lshl_add_u64 v[12:13], v[10:11], 0, s[22:23]
	v_lshl_add_u64 v[18:19], v[12:13], 0, s[22:23]
	v_lshl_add_u64 v[20:21], v[18:19], 0, s[22:23]
	v_lshl_add_u64 v[26:27], v[20:21], 0, s[22:23]
	v_lshl_add_u64 v[28:29], v[26:27], 0, s[22:23]
	v_lshl_add_u64 v[38:39], v[28:29], 0, s[22:23]
	global_load_dwordx4 v[2:5], v[10:11], off sc0 sc1 nt
	global_load_dwordx4 v[6:9], v[12:13], off sc0 sc1 nt
	s_nop 0
	global_load_dwordx4 v[10:13], v[18:19], off sc0 sc1 nt
	global_load_dwordx4 v[14:17], v[20:21], off sc0 sc1 nt
	s_nop 0
	global_load_dwordx4 v[18:21], v[26:27], off sc0 sc1 nt
	global_load_dwordx4 v[22:25], v[28:29], off sc0 sc1 nt
	s_nop 0
	global_load_dwordx4 v[26:29], v[38:39], off sc0 sc1 nt
	global_load_dwordx4 v[30:33], v[34:35], off sc0 sc1 nt
	v_lshlrev_b32_e32 v34, 3, v80
	v_and_or_b32 v82, v34, 24, v37
	v_and_b32_e32 v34, 7, v36
	v_lshl_add_u32 v35, v34, 4, s24
	v_lshlrev_b32_e32 v66, 3, v34
	v_mul_u32_u24_e32 v34, 0x420, v34
	v_mov_b32_e32 v69, 0
	v_mul_u32_u24_e32 v36, 0x84, v81
	v_lshlrev_b32_e32 v37, 2, v81
	v_lshlrev_b32_e32 v70, 12, v81
	v_mov_b32_e32 v67, v69
	v_or_b32_e32 v83, 0x2000, v82
	v_add3_u32 v84, s24, v34, v37
	v_mov_b32_e32 v71, v69
	v_or_b32_e32 v72, 0x8000, v70
	v_mov_b32_e32 v73, v69
	v_or_b32_e32 v74, 0x10000, v70
	v_mov_b32_e32 v75, v69
	s_mov_b32 s48, 0x18000
	v_or_b32_e32 v76, 0x18000, v70
	v_mov_b32_e32 v77, v69
	s_movk_i32 s49, 0x800
	v_add_u32_e32 v85, v35, v36
	s_mov_b32 s50, s3
	s_waitcnt vmcnt(0)
	s_branch .LBB0_39

; #define LAS __attribute__((address_space(3)))
; __device__ __forceinline__ void t_load(const TItem& t, f32x4 (&v)[8]) {
; #pragma unroll
;     for (int j = 0; j < 8; ++j) v[j] = __builtin_nontemporal_load((const f32x4*)(t.src + (size_t)(8 * j) * t.N));
; }
; __device__ __forceinline__ void p0_prologue(const Ptrs& P, LAS unsigned char* lds, int vcu, int G, int tid) {
;     ...
;             const TItem nxt = t_decode(P, has_n ? nit : it, lane); t_load(nxt, nv);
;             const int c4 = 4 * (lane & 7), r8 = lane >> 3;
; #pragma unroll
;             for (int j = 0; j < 8; ++j) { LAS float* d = scr + (8 * j + r8) * 33 + c4; d[0] = v[j][0]; d[1] = v[j][1]; d[2] = v[j][2]; d[3] = v[j][3]; }
;             asm volatile("s_waitcnt lgkmcnt(0)" ::: "memory");
;             const int c = lane & 7;
;             if (cur.f8) {
; #pragma unroll
;                 for (int j = 0; j < 4; ++j) { const int n = (lane >> 3) + 8 * j; const LAS float* sp = scr + (8 * c) * 33 + n;
;                     int w0 = 0, w1 = 0;
;                     w0 = __builtin_amdgcn_cvt_pk_fp8_f32(sp[0 * 33] * F8_SW, sp[1 * 33] * F8_SW, w0, false); w0 = __builtin_amdgcn_cvt_pk_fp8_f32(sp[2 * 33] * F8_SW, sp[3 * 33] * F8_SW, w0, true);
;                     w1 = __builtin_amdgcn_cvt_pk_fp8_f32(sp[4 * 33] * F8_SW, sp[5 * 33] * F8_SW, w1, false); w1 = __builtin_amdgcn_cvt_pk_fp8_f32(sp[6 * 33] * F8_SW, sp[7 * 33] * F8_SW, w1, true);
;                     u32x2 o; o.x = (unsigned)w0; o.y = (unsigned)w1;
;                     *(u32x2*)((unsigned char*)cur.dst + (size_t)n * cur.ldk + 8 * c) = o; }
.LBB0_62:
	s_lshl_b32 s20, s26, 5
	v_lshl_add_u64 v[42:43], v[78:79], 0, s[20:21]
	v_lshl_add_u64 v[44:45], v[42:43], 0, s[20:21]
	v_lshl_add_u64 v[50:51], v[44:45], 0, s[20:21]
	v_lshl_add_u64 v[52:53], v[50:51], 0, s[20:21]
	v_lshl_add_u64 v[58:59], v[52:53], 0, s[20:21]
	v_lshl_add_u64 v[60:61], v[58:59], 0, s[20:21]
	global_load_dwordx4 v[34:37], v[42:43], off sc0 sc1 nt
	global_load_dwordx4 v[38:41], v[44:45], off sc0 sc1 nt
	s_nop 0
	global_load_dwordx4 v[42:45], v[50:51], off sc0 sc1 nt
	global_load_dwordx4 v[46:49], v[52:53], off sc0 sc1 nt
	s_nop 0
	global_load_dwordx4 v[50:53], v[58:59], off sc0 sc1 nt
	global_load_dwordx4 v[54:57], v[60:61], off sc0 sc1 nt
	v_lshl_add_u64 v[86:87], v[60:61], 0, s[20:21]
	global_load_dwordx4 v[62:65], v[78:79], off sc0 sc1 nt
	global_load_dwordx4 v[58:61], v[86:87], off sc0 sc1 nt
	s_waitcnt vmcnt(12)
	ds_write2_b32 v85, v30, v31 offset1:1
	ds_write2_b32 v85, v32, v33 offset0:2 offset1:3
	v_add_u32_e32 v30, 0x420, v85
	ds_write2_b32 v30, v26, v27 offset1:1
	v_add_u32_e32 v26, 0x428, v85
	ds_write2_b32 v26, v28, v29 offset1:1
	v_add_u32_e32 v26, 0x840, v85
	ds_write2_b32 v26, v22, v23 offset1:1
	v_add_u32_e32 v22, 0x848, v85
	ds_write2_b32 v22, v24, v25 offset1:1
	v_add_u32_e32 v22, 0xc60, v85
	ds_write2_b32 v22, v18, v19 offset1:1
	v_add_u32_e32 v18, 0xc68, v85
	ds_write2_b32 v18, v20, v21 offset1:1
	v_add_u32_e32 v18, 0x1080, v85
	ds_write2_b32 v18, v14, v15 offset1:1
	v_add_u32_e32 v14, 0x1088, v85
	ds_write2_b32 v14, v16, v17 offset1:1
	v_add_u32_e32 v14, 0x14a0, v85
	ds_write2_b32 v14, v10, v11 offset1:1
	v_add_u32_e32 v10, 0x14a8, v85
	ds_write2_b32 v10, v12, v13 offset1:1
	v_add_u32_e32 v10, 0x18c0, v85
	ds_write2_b32 v10, v6, v7 offset1:1
	v_add_u32_e32 v6, 0x18c8, v85
	ds_write2_b32 v6, v8, v9 offset1:1
	v_add_u32_e32 v6, 0x1ce0, v85
	ds_write2_b32 v6, v2, v3 offset1:1
	v_add_u32_e32 v2, 0x1ce8, v85
	ds_write2_b32 v2, v4, v5 offset1:1
	s_waitcnt lgkmcnt(0)
	ds_read_b32 v2, v84
	s_cmp_eq_u32 s51, 0
	s_cbranch_scc1 .LBB0_64
	ds_read2_b32 v[4:5], v84 offset0:24 offset1:33
	ds_read2_b32 v[10:11], v84 offset0:57 offset1:66
	ds_read2_b32 v[12:13], v84 offset0:90 offset1:99
	s_waitcnt lgkmcnt(3)
	v_mul_f32_e32 v3, 0x43800000, v2
	v_mov_b32_e32 v8, v69
	s_waitcnt lgkmcnt(2)
	v_mul_f32_e32 v5, 0x43800000, v5
	ds_read2_b32 v[14:15], v84 offset0:123 offset1:132
	ds_read2_b32 v[16:17], v84 offset0:156 offset1:165
	v_cvt_pk_fp8_f32 v8, v3, v5
	s_waitcnt lgkmcnt(3)
	v_mul_f32_e32 v3, 0x43800000, v11
	s_waitcnt lgkmcnt(2)
	v_mul_f32_e32 v5, 0x43800000, v13
	ds_read2_b32 v[18:19], v84 offset0:189 offset1:198
	ds_read2_b32 v[20:21], v84 offset0:222 offset1:231
	v_cvt_pk_fp8_f32 v8, v3, v5 op_sel:[0,0,1]
	s_waitcnt lgkmcnt(3)
	v_mul_f32_e32 v3, 0x43800000, v15
	s_waitcnt lgkmcnt(2)
	v_mul_f32_e32 v5, 0x43800000, v17
	v_mov_b32_e32 v9, v69
	ds_read2_b32 v[22:23], v84 offset0:8 offset1:16
	ds_read2_b32 v[24:25], v84 offset0:41 offset1:49
	v_cvt_pk_fp8_f32 v9, v3, v5
	ds_read2_b32 v[28:29], v84 offset0:74 offset1:82
	ds_read2_b32 v[30:31], v84 offset0:107 offset1:115
	ds_read2_b32 v[32:33], v84 offset0:140 offset1:148
	ds_read2_b32 v[78:79], v84 offset0:173 offset1:181
	s_waitcnt lgkmcnt(7)
	v_mul_f32_e32 v3, 0x43800000, v19
	s_waitcnt lgkmcnt(6)
	v_mul_f32_e32 v5, 0x43800000, v21
	v_cvt_pk_fp8_f32 v9, v3, v5 op_sel:[0,0,1]
	s_waitcnt lgkmcnt(5)
	v_mul_f32_e32 v3, 0x43800000, v22
	s_waitcnt lgkmcnt(4)
	v_mul_f32_e32 v5, 0x43800000, v24
	v_mov_b32_e32 v26, v69
	ds_read2_b32 v[86:87], v84 offset0:206 offset1:214
	ds_read2_b32 v[88:89], v84 offset0:239 offset1:247
	v_cvt_pk_fp8_f32 v26, v3, v5
	s_waitcnt lgkmcnt(3)
	v_mul_f32_e32 v11, 0x43800000, v32
	s_waitcnt lgkmcnt(2)
	v_mul_f32_e32 v13, 0x43800000, v78
	v_mov_b32_e32 v27, v69
	v_cvt_pk_fp8_f32 v27, v11, v13
	v_mul_f32_e32 v3, 0x43800000, v28
	v_mul_f32_e32 v5, 0x43800000, v30
	v_cvt_pk_fp8_f32 v26, v3, v5 op_sel:[0,0,1]
	s_waitcnt lgkmcnt(1)
	v_mul_f32_e32 v3, 0x43800000, v86
	s_waitcnt lgkmcnt(0)
	v_mul_f32_e32 v5, 0x43800000, v88
	v_cvt_pk_fp8_f32 v27, v3, v5 op_sel:[0,0,1]
	v_lshl_add_u64 v[6:7], s[18:19], 0, v[66:67]
	v_lshl_add_u64 v[92:93], v[6:7], 0, v[70:71]
	global_store_dwordx2 v[92:93], v[8:9], off sc1
	v_lshl_add_u64 v[8:9], v[6:7], 0, v[72:73]
	global_store_dwordx2 v[8:9], v[26:27], off sc1
	v_mul_f32_e32 v3, 0x43800000, v23
	v_mul_f32_e32 v5, 0x43800000, v25
	v_mov_b32_e32 v8, v69
	v_cvt_pk_fp8_f32 v8, v3, v5
	v_mul_f32_e32 v11, 0x43800000, v33
	v_mul_f32_e32 v13, 0x43800000, v79
	v_mov_b32_e32 v9, v69
	v_cvt_pk_fp8_f32 v9, v11, v13
	v_mul_f32_e32 v3, 0x43800000, v29
	v_mul_f32_e32 v5, 0x43800000, v31
	v_cvt_pk_fp8_f32 v8, v3, v5 op_sel:[0,0,1]
	v_mul_f32_e32 v3, 0x43800000, v87
	v_mul_f32_e32 v5, 0x43800000, v89
	v_cvt_pk_fp8_f32 v9, v3, v5 op_sel:[0,0,1]
	v_mul_f32_e32 v3, 0x43800000, v4
	v_mul_f32_e32 v5, 0x43800000, v10
	v_mov_b32_e32 v4, v69
	ds_read_b32 v13, v84 offset:1020
	v_cvt_pk_fp8_f32 v4, v3, v5
	v_mul_f32_e32 v3, 0x43800000, v12
	v_mul_f32_e32 v11, 0x43800000, v16
	v_mul_f32_e32 v12, 0x43800000, v18
	v_mov_b32_e32 v5, v69
	v_cvt_pk_fp8_f32 v5, v11, v12
	v_mul_f32_e32 v10, 0x43800000, v14
	v_cvt_pk_fp8_f32 v4, v3, v10 op_sel:[0,0,1]
	v_mul_f32_e32 v3, 0x43800000, v20
	s_waitcnt lgkmcnt(0)
	v_mul_f32_e32 v10, 0x43800000, v13
	v_cvt_pk_fp8_f32 v5, v3, v10 op_sel:[0,0,1]
	v_lshl_add_u64 v[10:11], v[6:7], 0, v[74:75]
	v_lshl_add_u64 v[6:7], v[6:7], 0, v[76:77]
	global_store_dwordx2 v[10:11], v[8:9], off sc1
	global_store_dwordx2 v[6:7], v[4:5], off sc1
	s_cbranch_execnz .LBB0_38
	s_branch .LBB0_37
